# v84 + grid-barrier spin loops poll with s_sleep 0 instead of s_sleep 1
# speedup vs baseline: 1.0001x; 1.0001x over previous
.LBB0_14:
	s_sleep 0
	global_load_dword v2, v0, s[4:5] offset:32 sc1
	s_waitcnt vmcnt(0)
	v_and_b32_e32 v2, 0xffff0000, v2
	v_cmp_ne_u32_e32 vcc, v2, v1
	s_or_b64 s[6:7], vcc, s[6:7]
	s_andn2_b64 exec, exec, s[6:7]
	s_cbranch_execnz .LBB0_14

.LBB0_377:
	global_load_dword v15, v16, s[8:9] sc1
	global_load_dword v0, v16, s[10:11] sc1
	global_load_dword v1, v16, s[12:13] sc1
	global_load_dword v2, v16, s[14:15] sc1
	global_load_dword v3, v16, s[24:25] sc1
	global_load_dword v4, v16, s[26:27] sc1
	global_load_dword v5, v16, s[28:29] sc1
	global_load_dword v6, v16, s[30:31] sc1
	global_load_dword v7, v16, s[34:35] sc1
	global_load_dword v8, v16, s[36:37] sc1
	global_load_dword v9, v16, s[38:39] sc1
	global_load_dword v10, v16, s[40:41] sc1
	global_load_dword v11, v16, s[42:43] sc1
	global_load_dword v12, v16, s[48:49] sc1
	global_load_dword v13, v16, s[50:51] sc1
	global_load_dword v14, v16, s[52:53] sc1
	s_mov_b64 s[54:55], -1
	s_mov_b64 s[56:57], -1
	s_waitcnt vmcnt(14)
	v_add_u32_e32 v17, v0, v15
	s_waitcnt vmcnt(13)
	v_add_u32_e32 v17, v17, v1
	s_waitcnt vmcnt(12)
	v_add_u32_e32 v17, v17, v2
	s_waitcnt vmcnt(11)
	v_add_u32_e32 v17, v17, v3
	s_waitcnt vmcnt(10)
	v_add_u32_e32 v17, v17, v4
	s_waitcnt vmcnt(9)
	v_add_u32_e32 v17, v17, v5
	s_waitcnt vmcnt(8)
	v_add_u32_e32 v17, v17, v6
	s_waitcnt vmcnt(7)
	v_add_u32_e32 v17, v17, v7
	s_waitcnt vmcnt(6)
	v_add_u32_e32 v17, v17, v8
	s_waitcnt vmcnt(5)
	v_add_u32_e32 v17, v17, v9
	s_waitcnt vmcnt(4)
	v_add_u32_e32 v17, v17, v10
	s_waitcnt vmcnt(3)
	v_add_u32_e32 v17, v17, v11
	s_waitcnt vmcnt(2)
	v_add_u32_e32 v17, v17, v12
	s_waitcnt vmcnt(1)
	v_add_u32_e32 v17, v17, v13
	s_waitcnt vmcnt(0)
	v_add_u32_e32 v17, v17, v14
	v_cmp_eq_u32_e32 vcc, s2, v17
	s_cbranch_vccnz .LBB0_376
	s_and_b32 s33, s3, 0xff
	s_cmp_eq_u32 s33, 0
	s_mov_b64 s[58:59], -1
	s_sleep 0
	s_cbranch_scc1 .LBB0_381
	s_and_b64 vcc, exec, s[58:59]
	s_cbranch_vccz .LBB0_376

.LBB0_395:
	s_and_b32 s3, s2, 0xff
	s_mov_b64 s[28:29], -1
	s_cmp_lg_u32 s3, 0
	s_mov_b64 s[34:35], -1
	s_sleep 0
	s_cbranch_scc0 .LBB0_398
	s_and_b64 vcc, exec, s[34:35]
	s_cbranch_vccz .LBB0_394

.LBB0_412:
	s_and_b32 s3, s2, 0xff
	s_cmp_lg_u32 s3, 0
	s_mov_b64 s[30:31], -1
	s_sleep 0
	s_cbranch_scc0 .LBB0_415
	s_mov_b64 s[34:35], -1
	s_and_b64 vcc, exec, s[30:31]
	s_cbranch_vccz .LBB0_411

.LBB0_646:
	global_load_dword v15, v16, s[8:9] sc1
	global_load_dword v0, v16, s[10:11] sc1
	global_load_dword v1, v16, s[12:13] sc1
	global_load_dword v2, v16, s[14:15] sc1
	global_load_dword v3, v16, s[16:17] sc1
	global_load_dword v4, v16, s[20:21] sc1
	global_load_dword v5, v16, s[22:23] sc1
	global_load_dword v6, v16, s[24:25] sc1
	global_load_dword v7, v16, s[26:27] sc1
	global_load_dword v8, v16, s[28:29] sc1
	global_load_dword v9, v16, s[30:31] sc1
	global_load_dword v10, v16, s[34:35] sc1
	global_load_dword v11, v16, s[36:37] sc1
	global_load_dword v12, v16, s[38:39] sc1
	global_load_dword v13, v16, s[40:41] sc1
	global_load_dword v14, v16, s[42:43] sc1
	s_mov_b64 s[44:45], -1
	s_mov_b64 s[46:47], -1
	s_waitcnt vmcnt(14)
	v_add_u32_e32 v17, v0, v15
	s_waitcnt vmcnt(13)
	v_add_u32_e32 v17, v17, v1
	s_waitcnt vmcnt(12)
	v_add_u32_e32 v17, v17, v2
	s_waitcnt vmcnt(11)
	v_add_u32_e32 v17, v17, v3
	s_waitcnt vmcnt(10)
	v_add_u32_e32 v17, v17, v4
	s_waitcnt vmcnt(9)
	v_add_u32_e32 v17, v17, v5
	s_waitcnt vmcnt(8)
	v_add_u32_e32 v17, v17, v6
	s_waitcnt vmcnt(7)
	v_add_u32_e32 v17, v17, v7
	s_waitcnt vmcnt(6)
	v_add_u32_e32 v17, v17, v8
	s_waitcnt vmcnt(5)
	v_add_u32_e32 v17, v17, v9
	s_waitcnt vmcnt(4)
	v_add_u32_e32 v17, v17, v10
	s_waitcnt vmcnt(3)
	v_add_u32_e32 v17, v17, v11
	s_waitcnt vmcnt(2)
	v_add_u32_e32 v17, v17, v12
	s_waitcnt vmcnt(1)
	v_add_u32_e32 v17, v17, v13
	s_waitcnt vmcnt(0)
	v_add_u32_e32 v17, v17, v14
	v_cmp_eq_u32_e32 vcc, s2, v17
	s_cbranch_vccnz .LBB0_645
	s_and_b32 s33, s3, 0xff
	s_cmp_eq_u32 s33, 0
	s_mov_b64 s[48:49], -1
	s_sleep 0
	s_cbranch_scc1 .LBB0_650
	s_and_b64 vcc, exec, s[48:49]
	s_cbranch_vccz .LBB0_645

.LBB0_664:
	s_and_b32 s3, s2, 0xff
	s_mov_b64 s[22:23], -1
	s_cmp_lg_u32 s3, 0
	s_mov_b64 s[26:27], -1
	s_sleep 0
	s_cbranch_scc0 .LBB0_667
	s_and_b64 vcc, exec, s[26:27]
	s_cbranch_vccz .LBB0_663

.LBB0_681:
	s_and_b32 s3, s2, 0xff
	s_cmp_lg_u32 s3, 0
	s_mov_b64 s[24:25], -1
	s_sleep 0
	s_cbranch_scc0 .LBB0_684
	s_mov_b64 s[26:27], -1
	s_and_b64 vcc, exec, s[24:25]
	s_cbranch_vccz .LBB0_680

.LBB0_1190:
	global_load_dword v15, v16, s[8:9] sc1
	global_load_dword v0, v16, s[10:11] sc1
	global_load_dword v1, v16, s[12:13] sc1
	global_load_dword v2, v16, s[14:15] sc1
	global_load_dword v3, v16, s[16:17] sc1
	global_load_dword v4, v16, s[18:19] sc1
	global_load_dword v5, v16, s[20:21] sc1
	global_load_dword v6, v16, s[22:23] sc1
	global_load_dword v7, v16, s[24:25] sc1
	global_load_dword v8, v16, s[26:27] sc1
	global_load_dword v9, v16, s[28:29] sc1
	global_load_dword v10, v16, s[30:31] sc1
	global_load_dword v11, v16, s[34:35] sc1
	global_load_dword v12, v16, s[36:37] sc1
	global_load_dword v13, v16, s[38:39] sc1
	global_load_dword v14, v16, s[40:41] sc1
	s_mov_b64 s[42:43], -1
	s_mov_b64 s[44:45], -1
	s_waitcnt vmcnt(14)
	v_add_u32_e32 v17, v0, v15
	s_waitcnt vmcnt(13)
	v_add_u32_e32 v17, v17, v1
	s_waitcnt vmcnt(12)
	v_add_u32_e32 v17, v17, v2
	s_waitcnt vmcnt(11)
	v_add_u32_e32 v17, v17, v3
	s_waitcnt vmcnt(10)
	v_add_u32_e32 v17, v17, v4
	s_waitcnt vmcnt(9)
	v_add_u32_e32 v17, v17, v5
	s_waitcnt vmcnt(8)
	v_add_u32_e32 v17, v17, v6
	s_waitcnt vmcnt(7)
	v_add_u32_e32 v17, v17, v7
	s_waitcnt vmcnt(6)
	v_add_u32_e32 v17, v17, v8
	s_waitcnt vmcnt(5)
	v_add_u32_e32 v17, v17, v9
	s_waitcnt vmcnt(4)
	v_add_u32_e32 v17, v17, v10
	s_waitcnt vmcnt(3)
	v_add_u32_e32 v17, v17, v11
	s_waitcnt vmcnt(2)
	v_add_u32_e32 v17, v17, v12
	s_waitcnt vmcnt(1)
	v_add_u32_e32 v17, v17, v13
	s_waitcnt vmcnt(0)
	v_add_u32_e32 v17, v17, v14
	v_cmp_eq_u32_e32 vcc, s2, v17
	s_cbranch_vccnz .LBB0_1189
	s_and_b32 s33, s3, 0xff
	s_cmp_eq_u32 s33, 0
	s_mov_b64 s[46:47], -1
	s_sleep 0
	s_cbranch_scc1 .LBB0_1194
	s_and_b64 vcc, exec, s[46:47]
	s_cbranch_vccz .LBB0_1189

.LBB0_1208:
	s_and_b32 s3, s2, 0xff
	s_mov_b64 s[20:21], -1
	s_cmp_lg_u32 s3, 0
	s_mov_b64 s[24:25], -1
	s_sleep 0
	s_cbranch_scc0 .LBB0_1211
	s_and_b64 vcc, exec, s[24:25]
	s_cbranch_vccz .LBB0_1207

.LBB0_1225:
	s_and_b32 s3, s2, 0xff
	s_cmp_lg_u32 s3, 0
	s_mov_b64 s[22:23], -1
	s_sleep 0
	s_cbranch_scc0 .LBB0_1228
	s_mov_b64 s[24:25], -1
	s_and_b64 vcc, exec, s[22:23]
	s_cbranch_vccz .LBB0_1224
